# norm phases P6/P9: the 512 context rows (with their K-slice partial sums) spread over all workgroups (row j -> wave 4j) instead of being the 9th row of waves 0..511 on workgroups 0..63
# speedup vs baseline: 1.0152x; 1.0074x over previous
; #define GAS __attribute__((address_space(1)))
;     ...
;     for (int m = gw; m < nrows; m += NGW) {
;         const float* xrow = m < ML ? src_lat + (size_t)m * DM : src_ctx + (size_t)(m - ML) * DM;
;         const int cnd = m < SEQ ? 0 : (m < ML ? 1 : 2);
;         const GAS f32x4* xr = (const GAS f32x4*)xrow + F.lane;
;         f32x4 v[4]; float s = 0.f;
;         if (lat_bf16 && m < ML) {
;     ...
;         for (int j = 0; j < 4; ++j) s += (v[j].x * v[j].x + v[j].y * v[j].y) + (v[j].z * v[j].z + v[j].w * v[j].w);
;         const float rstd = 1.f / sqrtf(wave_sum(s, F.lane) * (1.f / DM) + NORM_EPS);
.LBB0_160:
	v_pk_mul_f32 v[38:39], v[32:33], v[32:33]
	v_pk_mul_f32 v[40:41], v[30:31], v[30:31]
	v_pk_mul_f32 v[34:35], v[28:29], v[28:29]
	v_pk_mul_f32 v[36:37], v[26:27], v[26:27]
	v_pk_mov_b32 v[42:43], v[40:41], v[38:39] op_sel:[1,0]
	v_mov_b32_e32 v41, v39
	v_pk_add_f32 v[38:39], v[42:43], v[40:41]
	v_pk_mov_b32 v[40:41], v[36:37], v[34:35] op_sel:[1,0]
	v_mov_b32_e32 v37, v35
	v_pk_add_f32 v[34:35], v[40:41], v[36:37]
	v_pk_add_f32 v[38:39], v[38:39], v[38:39] op_sel_hi:[0,1]
	v_pk_add_f32 v[34:35], v[34:35], v[34:35] op_sel_hi:[0,1]
	v_mul_f32_e32 v34, v22, v22
	v_pk_fma_f32 v[36:37], v[22:23], v[22:23], v[34:35] op_sel_hi:[1,1,0]
	v_mul_f32_e32 v34, v24, v24
	v_pk_fma_f32 v[40:41], v[24:25], v[24:25], v[34:35] op_sel_hi:[1,1,0]
	v_mul_f32_e32 v36, v18, v18
	v_mul_f32_e32 v40, v19, v19
	v_mul_f32_e32 v38, v20, v20
	v_mul_f32_e32 v34, v21, v21
	v_pk_add_f32 v[36:37], v[36:37], v[40:41]
	v_pk_add_f32 v[34:35], v[38:39], v[34:35]
	s_and_b64 s[4:5], exec, s[4:5]
	v_pk_add_f32 v[34:35], v[36:37], v[34:35]
	s_movk_i32 s1, 0x800
	v_add_f32_e32 v34, v34, v35
	s_cselect_b32 s1, 0x400, s1
	s_cmpk_gt_i32 s0, 0x1fff
	v_add_f32_dpp v34, v34, v34 row_ror:8 row_mask:0xf bank_mask:0xf bound_ctrl:1
	s_cselect_b32 s1, s1, 0
	v_lshl_add_u64 v[44:45], s[8:9], 0, v[84:85]
	v_add_f32_dpp v34, v34, v34 row_ror:4 row_mask:0xf bank_mask:0xf bound_ctrl:1
	s_add_i32 s0, s0, s6
	s_add_u32 s8, s8, s10
	v_add_f32_dpp v34, v34, v34 row_ror:2 row_mask:0xf bank_mask:0xf bound_ctrl:1
	s_addc_u32 s9, s9, s11
	s_add_u32 s12, s12, s10
	v_add_f32_dpp v34, v34, v34 row_ror:1 row_mask:0xf bank_mask:0xf bound_ctrl:1
	s_addc_u32 s13, s13, s11
	s_cmpk_lt_i32 s0, 0x4000
	s_cbranch_scc1 .Lcs_a_done
	s_sub_i32 s98, s0, 0x4000
	s_and_b32 s99, s98, 3
	s_cmp_lg_u32 s99, 0
	s_cbranch_scc1 .Lcs_a_none
	s_lshr_b32 s99, s98, 2
	s_sub_i32 s98, s99, s98
	s_add_i32 s0, s99, 0x4000
	s_lshl_b32 s98, s98, 11
	s_ashr_i32 s99, s98, 31
	s_add_u32 s8, s8, s98
	s_addc_u32 s9, s9, s99
	s_branch .Lcs_a_done
.Lcs_a_none:
	s_movk_i32 s0, 0x7000
.Lcs_a_done:
	s_cmpk_lt_i32 s0, 0x4000
	s_cbranch_scc0 .Ln3a_nopf
	v_lshl_add_u64 v[228:229], s[12:13], 0, v[84:85]
	global_load_dwordx2 v[220:221], v[228:229], off
	global_load_dwordx2 v[222:223], v[228:229], off offset:512
	global_load_dwordx2 v[224:225], v[228:229], off offset:1024
	global_load_dwordx2 v[226:227], v[228:229], off offset:1536

; #define WS_ROR(x, n) __builtin_bit_cast(float, __builtin_amdgcn_update_dpp(0, __builtin_bit_cast(int, x), 0x120 | (n), 0xf, 0xf, false))
; __device__ __forceinline__ float wave_sum(float v, int lane) {
;     (void)lane;
;     ...
;     v += WS_ROR(v, 8); v += WS_ROR(v, 4); v += WS_ROR(v, 2); v += WS_ROR(v, 1);
;     ...
;     const int b = __builtin_bit_cast(int, v);
;     return (__builtin_bit_cast(float, __builtin_amdgcn_readlane(b, 0)) + __builtin_bit_cast(float, __builtin_amdgcn_readlane(b, 16))) + (__builtin_bit_cast(float, __builtin_amdgcn_readlane(b, 32)) + __builtin_bit_cast(float, __builtin_amdgcn_readlane(b, 48)));
;     ...
;         for (int j = 0; j < 4; ++j) s += (v[j].x * v[j].x + v[j].y * v[j].y) + (v[j].z * v[j].z + v[j].w * v[j].w);
;         const float rstd = 1.f / sqrtf(wave_sum(s, F.lane) * (1.f / DM) + NORM_EPS);
.LBB0_194:
	v_pk_mul_f32 v[44:45], v[32:33], v[32:33]
	v_pk_mul_f32 v[46:47], v[30:31], v[30:31]
	v_pk_mul_f32 v[40:41], v[28:29], v[28:29]
	v_pk_mul_f32 v[42:43], v[26:27], v[26:27]
	v_pk_mov_b32 v[48:49], v[46:47], v[44:45] op_sel:[1,0]
	v_mov_b32_e32 v47, v45
	v_pk_add_f32 v[44:45], v[48:49], v[46:47]
	v_pk_mov_b32 v[46:47], v[42:43], v[40:41] op_sel:[1,0]
	v_mov_b32_e32 v43, v41
	v_mul_f32_e32 v38, v22, v22
	v_pk_add_f32 v[40:41], v[46:47], v[42:43]
	v_pk_fma_f32 v[42:43], v[22:23], v[22:23], v[38:39] op_sel_hi:[1,1,0]
	v_mul_f32_e32 v38, v24, v24
	v_pk_add_f32 v[44:45], v[44:45], v[44:45] op_sel_hi:[0,1]
	v_pk_add_f32 v[40:41], v[40:41], v[40:41] op_sel_hi:[0,1]
	v_pk_fma_f32 v[46:47], v[24:25], v[24:25], v[38:39] op_sel_hi:[1,1,0]
	v_mul_f32_e32 v42, v18, v18
	v_mul_f32_e32 v46, v19, v19
	v_mul_f32_e32 v44, v20, v20
	v_mul_f32_e32 v40, v21, v21
	v_pk_add_f32 v[42:43], v[42:43], v[46:47]
	v_pk_add_f32 v[40:41], v[44:45], v[40:41]
	s_and_b64 s[4:5], exec, s[4:5]
	v_pk_add_f32 v[40:41], v[42:43], v[40:41]
	s_movk_i32 s1, 0x800
	v_add_f32_e32 v38, v40, v41
	s_cselect_b32 s1, 0x400, s1
	s_cmpk_gt_i32 s0, 0x1fff
	v_add_f32_dpp v38, v38, v38 row_ror:8 row_mask:0xf bank_mask:0xf bound_ctrl:1
	s_cselect_b32 s1, s1, 0
	v_lshl_add_u32 v50, s1, 2, v39
	v_add_f32_dpp v38, v38, v38 row_ror:4 row_mask:0xf bank_mask:0xf bound_ctrl:1
	s_mov_b32 s1, 0xffff0000
	v_lshl_add_u64 v[48:49], s[10:11], 0, v[0:1]
	v_add_f32_dpp v38, v38, v38 row_ror:2 row_mask:0xf bank_mask:0xf bound_ctrl:1
	s_add_i32 s0, s0, s8
	s_add_u32 s10, s10, s12
	v_add_f32_dpp v38, v38, v38 row_ror:1 row_mask:0xf bank_mask:0xf bound_ctrl:1
	s_addc_u32 s11, s11, s13
	v_readlane_b32 s9, v38, 16
	v_readlane_b32 s16, v38, 48
	v_readlane_b32 s4, v38, 0
	v_readlane_b32 s5, v38, 32
	v_mov_b32_e32 v40, s9
	v_mov_b32_e32 v41, s16
	v_pk_add_f32 v[40:41], s[4:5], v[40:41]
	s_mov_b32 s4, 0xf800000
	v_add_f32_e32 v38, v40, v41
	v_fmamk_f32 v38, v38, 0x3a800000, v173
	v_cmp_gt_f32_e32 vcc, s4, v38
	v_mul_f32_e32 v40, 0x4f800000, v38
	s_add_u32 s14, s14, s12
	v_cndmask_b32_e32 v38, v38, v40, vcc
	v_sqrt_f32_e32 v40, v38
	s_addc_u32 s15, s15, s13
	s_cmpk_lt_i32 s0, 0x4000
	s_cbranch_scc1 .Lcs_b_done
	s_sub_i32 s98, s0, 0x4000
	s_and_b32 s99, s98, 3
	s_cmp_lg_u32 s99, 0
	s_cbranch_scc1 .Lcs_b_none
	s_lshr_b32 s99, s98, 2
	s_sub_i32 s98, s99, s98
	s_add_i32 s0, s99, 0x4000
	s_lshl_b32 s98, s98, 11
	s_ashr_i32 s99, s98, 31
	s_add_u32 s10, s10, s98
	s_addc_u32 s11, s11, s99
	s_branch .Lcs_b_done

; #define GAS __attribute__((address_space(1)))
;     ...
;     for (int m = gw; m < nrows; m += NGW) {
;         const float* xrow = m < ML ? src_lat + (size_t)m * DM : src_ctx + (size_t)(m - ML) * DM;
;         const int cnd = m < SEQ ? 0 : (m < ML ? 1 : 2);
;         const GAS f32x4* xr = (const GAS f32x4*)xrow + F.lane;
;         f32x4 v[4]; float s = 0.f;
;         if (lat_bf16 && m < ML) {
;             const GAS v2u* xb = (const GAS v2u*)((const bf16*)src_lat + (size_t)m * DM) + F.lane;
;             v2u w[4];
; #pragma unroll
;             for (int j = 0; j < 4; ++j) w[j] = xb[64 * j];
; #pragma unroll
;             for (int j = 0; j < 4; ++j) v[j] = f32x4{bflo(w[j].x), bfhi(w[j].x), bflo(w[j].y), bfhi(w[j].y)};
;         } else {
; #pragma unroll
;             for (int j = 0; j < 4; ++j) v[j] = xr[64 * j];
;         }
.Lcs_b_done:
	s_cmpk_lt_i32 s0, 0x4000
	s_cbranch_scc0 .Ln3b_nopf
	v_lshl_add_u64 v[228:229], s[14:15], 0, v[0:1]
	global_load_dwordx2 v[220:221], v[228:229], off
	global_load_dwordx2 v[222:223], v[228:229], off offset:512
	global_load_dwordx2 v[224:225], v[228:229], off offset:1024
	global_load_dwordx2 v[226:227], v[228:229], off offset:1536
